# P1s row loop processes four rows per trip with all eight loads issued first (was one row per trip with a full wait); original loop kept as tail
# baseline (speedup 1.0000x reference)
.Lp1s_quad:
	s_mul_i32 s36, s90, 3
	s_add_i32 s36, s36, s18
	s_cmp_gt_i32 s36, 0xffff
	s_cbranch_scc1 .LBB0_258
	s_add_u32 s38, s8, s10
	s_addc_u32 s39, s9, s11
	s_add_u32 s40, s38, s10
	s_addc_u32 s41, s39, s11
	s_add_u32 s42, s40, s10
	s_addc_u32 s43, s41, s11
	s_mov_b32 s37, s18
	s_and_b32 s0, s37, 0x1fff
	s_cmp_eq_u32 s0, 0
	s_cselect_b64 s[52:53], -1, 0
	s_cselect_b32 s0, 0, 0xfffffe00
	s_cselect_b32 s1, 0, -1
	s_add_u32 s44, s8, s0
	s_addc_u32 s45, s9, s1
	s_add_i32 s37, s37, s90
	s_and_b32 s0, s37, 0x1fff
	s_cmp_eq_u32 s0, 0
	s_cselect_b64 s[58:59], -1, 0
	s_cselect_b32 s0, 0, 0xfffffe00
	s_cselect_b32 s1, 0, -1
	s_add_u32 s46, s38, s0
	s_addc_u32 s47, s39, s1
	s_add_i32 s37, s37, s90
	s_and_b32 s0, s37, 0x1fff
	s_cmp_eq_u32 s0, 0
	s_cselect_b64 s[64:65], -1, 0
	s_cselect_b32 s0, 0, 0xfffffe00
	s_cselect_b32 s1, 0, -1
	s_add_u32 s48, s40, s0
	s_addc_u32 s49, s41, s1
	s_add_i32 s37, s37, s90
	s_and_b32 s0, s37, 0x1fff
	s_cmp_eq_u32 s0, 0
	s_cselect_b64 s[66:67], -1, 0
	s_cselect_b32 s0, 0, 0xfffffe00
	s_cselect_b32 s1, 0, -1
	s_add_u32 s50, s42, s0
	s_addc_u32 s51, s43, s1
	s_add_i32 s37, s37, s90
	global_load_dword v28, v0, s[8:9]
	global_load_dword v32, v4, s[44:45]
	global_load_dword v29, v0, s[38:39]
	global_load_dword v33, v4, s[46:47]
	global_load_dword v30, v0, s[40:41]
	global_load_dword v34, v4, s[48:49]
	global_load_dword v31, v0, s[42:43]
	global_load_dword v35, v4, s[50:51]
	s_waitcnt vmcnt(6)
	v_lshlrev_b32_e32 v7, 16, v28
	v_and_b32_e32 v6, 0xffff0000, v28
	v_lshlrev_b32_e32 v9, 16, v32
	v_and_b32_e32 v8, 0xffff0000, v32
	v_pk_add_f32 v[8:9], v[6:7], v[8:9]
	s_nop 0
	v_cndmask_b32_e64 v7, v9, v7, s[52:53]
	v_cndmask_b32_e64 v6, v8, v6, s[52:53]
	s_and_saveexec_b64 s[0:1], s[6:7]
	v_add_f32_e32 v7, v7, v7
	v_add_f32_e32 v6, v6, v6
	v_mul_f32_e32 v7, 0x3fb8aa3b, v7
	v_mul_f32_e32 v6, 0x3fb8aa3b, v6
	v_exp_f32_e32 v7, v7
	v_exp_f32_e32 v6, v6
	s_nop 0
	v_pk_add_f32 v[6:7], v[6:7], 1.0 op_sel_hi:[1,0]
	s_nop 0
	v_div_scale_f32 v8, s[20:21], v7, v7, -2.0
	v_rcp_f32_e32 v9, v8
	v_div_scale_f32 v10, vcc, -2.0, v7, -2.0
	v_fma_f32 v11, -v8, v9, 1.0
	v_fmac_f32_e32 v9, v11, v9
	v_mul_f32_e32 v11, v10, v9
	v_fma_f32 v12, -v8, v11, v10
	v_fmac_f32_e32 v11, v12, v9
	v_fma_f32 v8, -v8, v11, v10
	v_div_scale_f32 v10, s[20:21], v6, v6, -2.0
	v_rcp_f32_e32 v12, v10
	v_div_fmas_f32 v8, v8, v9, v11
	v_div_fixup_f32 v7, v8, v7, -2.0
	v_fma_f32 v8, -v10, v12, 1.0
	v_fmac_f32_e32 v12, v8, v12
	v_div_scale_f32 v8, vcc, -2.0, v6, -2.0
	v_mul_f32_e32 v9, v8, v12
	v_fma_f32 v11, -v10, v9, v8
	v_fmac_f32_e32 v9, v11, v12
	v_fma_f32 v8, -v10, v9, v8
	v_div_fmas_f32 v8, v8, v12, v9
	v_div_fixup_f32 v6, v8, v6, -2.0
	v_pk_add_f32 v[6:7], v[6:7], 1.0 op_sel_hi:[1,0]
	s_or_b64 exec, exec, s[0:1]
	s_nop 0
	v_cvt_pk_bf16_f32 v6, v7, v6
	global_store_dword v[2:3], v6, off
	v_lshl_add_u64 v[2:3], v[2:3], 0, s[4:5]
	s_waitcnt vmcnt(5)
	v_lshlrev_b32_e32 v7, 16, v29
	v_and_b32_e32 v6, 0xffff0000, v29
	v_lshlrev_b32_e32 v9, 16, v33
	v_and_b32_e32 v8, 0xffff0000, v33
	v_pk_add_f32 v[8:9], v[6:7], v[8:9]
	s_nop 0
	v_cndmask_b32_e64 v7, v9, v7, s[58:59]
	v_cndmask_b32_e64 v6, v8, v6, s[58:59]
	s_and_saveexec_b64 s[0:1], s[6:7]
	v_add_f32_e32 v7, v7, v7
	v_add_f32_e32 v6, v6, v6
	v_mul_f32_e32 v7, 0x3fb8aa3b, v7
	v_mul_f32_e32 v6, 0x3fb8aa3b, v6
	v_exp_f32_e32 v7, v7
	v_exp_f32_e32 v6, v6
	s_nop 0
	v_pk_add_f32 v[6:7], v[6:7], 1.0 op_sel_hi:[1,0]
	s_nop 0
	v_div_scale_f32 v8, s[20:21], v7, v7, -2.0
	v_rcp_f32_e32 v9, v8
	v_div_scale_f32 v10, vcc, -2.0, v7, -2.0
	v_fma_f32 v11, -v8, v9, 1.0
	v_fmac_f32_e32 v9, v11, v9
	v_mul_f32_e32 v11, v10, v9
	v_fma_f32 v12, -v8, v11, v10
	v_fmac_f32_e32 v11, v12, v9
	v_fma_f32 v8, -v8, v11, v10
	v_div_scale_f32 v10, s[20:21], v6, v6, -2.0
	v_rcp_f32_e32 v12, v10
	v_div_fmas_f32 v8, v8, v9, v11
	v_div_fixup_f32 v7, v8, v7, -2.0
	v_fma_f32 v8, -v10, v12, 1.0
	v_fmac_f32_e32 v12, v8, v12
	v_div_scale_f32 v8, vcc, -2.0, v6, -2.0
	v_mul_f32_e32 v9, v8, v12
	v_fma_f32 v11, -v10, v9, v8
	v_fmac_f32_e32 v9, v11, v12
	v_fma_f32 v8, -v10, v9, v8
	v_div_fmas_f32 v8, v8, v12, v9
	v_div_fixup_f32 v6, v8, v6, -2.0
	v_pk_add_f32 v[6:7], v[6:7], 1.0 op_sel_hi:[1,0]
	s_or_b64 exec, exec, s[0:1]
	s_nop 0
	v_cvt_pk_bf16_f32 v6, v7, v6
	global_store_dword v[2:3], v6, off
	v_lshl_add_u64 v[2:3], v[2:3], 0, s[4:5]
	s_waitcnt vmcnt(4)
	v_lshlrev_b32_e32 v7, 16, v30
	v_and_b32_e32 v6, 0xffff0000, v30
	v_lshlrev_b32_e32 v9, 16, v34
	v_and_b32_e32 v8, 0xffff0000, v34
	v_pk_add_f32 v[8:9], v[6:7], v[8:9]
	s_nop 0
	v_cndmask_b32_e64 v7, v9, v7, s[64:65]
	v_cndmask_b32_e64 v6, v8, v6, s[64:65]
	s_and_saveexec_b64 s[0:1], s[6:7]
	v_add_f32_e32 v7, v7, v7
	v_add_f32_e32 v6, v6, v6
	v_mul_f32_e32 v7, 0x3fb8aa3b, v7
	v_mul_f32_e32 v6, 0x3fb8aa3b, v6
	v_exp_f32_e32 v7, v7
	v_exp_f32_e32 v6, v6
	s_nop 0
	v_pk_add_f32 v[6:7], v[6:7], 1.0 op_sel_hi:[1,0]
	s_nop 0
	v_div_scale_f32 v8, s[20:21], v7, v7, -2.0
	v_rcp_f32_e32 v9, v8
	v_div_scale_f32 v10, vcc, -2.0, v7, -2.0
	v_fma_f32 v11, -v8, v9, 1.0
	v_fmac_f32_e32 v9, v11, v9
	v_mul_f32_e32 v11, v10, v9
	v_fma_f32 v12, -v8, v11, v10
	v_fmac_f32_e32 v11, v12, v9
	v_fma_f32 v8, -v8, v11, v10
	v_div_scale_f32 v10, s[20:21], v6, v6, -2.0
	v_rcp_f32_e32 v12, v10
	v_div_fmas_f32 v8, v8, v9, v11
	v_div_fixup_f32 v7, v8, v7, -2.0
	v_fma_f32 v8, -v10, v12, 1.0
	v_fmac_f32_e32 v12, v8, v12
	v_div_scale_f32 v8, vcc, -2.0, v6, -2.0
	v_mul_f32_e32 v9, v8, v12
	v_fma_f32 v11, -v10, v9, v8
	v_fmac_f32_e32 v9, v11, v12
	v_fma_f32 v8, -v10, v9, v8
	v_div_fmas_f32 v8, v8, v12, v9
	v_div_fixup_f32 v6, v8, v6, -2.0
	v_pk_add_f32 v[6:7], v[6:7], 1.0 op_sel_hi:[1,0]
	s_or_b64 exec, exec, s[0:1]
	s_nop 0
	v_cvt_pk_bf16_f32 v6, v7, v6
	global_store_dword v[2:3], v6, off
	v_lshl_add_u64 v[2:3], v[2:3], 0, s[4:5]
	s_waitcnt vmcnt(3)
	v_lshlrev_b32_e32 v7, 16, v31
	v_and_b32_e32 v6, 0xffff0000, v31
	v_lshlrev_b32_e32 v9, 16, v35
	v_and_b32_e32 v8, 0xffff0000, v35
	v_pk_add_f32 v[8:9], v[6:7], v[8:9]
	s_nop 0
	v_cndmask_b32_e64 v7, v9, v7, s[66:67]
	v_cndmask_b32_e64 v6, v8, v6, s[66:67]
	s_and_saveexec_b64 s[0:1], s[6:7]
	v_add_f32_e32 v7, v7, v7
	v_add_f32_e32 v6, v6, v6
	v_mul_f32_e32 v7, 0x3fb8aa3b, v7
	v_mul_f32_e32 v6, 0x3fb8aa3b, v6
	v_exp_f32_e32 v7, v7
	v_exp_f32_e32 v6, v6
	s_nop 0
	v_pk_add_f32 v[6:7], v[6:7], 1.0 op_sel_hi:[1,0]
	s_nop 0
	v_div_scale_f32 v8, s[20:21], v7, v7, -2.0
	v_rcp_f32_e32 v9, v8
	v_div_scale_f32 v10, vcc, -2.0, v7, -2.0
	v_fma_f32 v11, -v8, v9, 1.0
	v_fmac_f32_e32 v9, v11, v9
	v_mul_f32_e32 v11, v10, v9
	v_fma_f32 v12, -v8, v11, v10
	v_fmac_f32_e32 v11, v12, v9
	v_fma_f32 v8, -v8, v11, v10
	v_div_scale_f32 v10, s[20:21], v6, v6, -2.0
	v_rcp_f32_e32 v12, v10
	v_div_fmas_f32 v8, v8, v9, v11
	v_div_fixup_f32 v7, v8, v7, -2.0
	v_fma_f32 v8, -v10, v12, 1.0
	v_fmac_f32_e32 v12, v8, v12
	v_div_scale_f32 v8, vcc, -2.0, v6, -2.0
	v_mul_f32_e32 v9, v8, v12
	v_fma_f32 v11, -v10, v9, v8
	v_fmac_f32_e32 v9, v11, v12
	v_fma_f32 v8, -v10, v9, v8
	v_div_fmas_f32 v8, v8, v12, v9
	v_div_fixup_f32 v6, v8, v6, -2.0
	v_pk_add_f32 v[6:7], v[6:7], 1.0 op_sel_hi:[1,0]
	s_or_b64 exec, exec, s[0:1]
	s_nop 0
	v_cvt_pk_bf16_f32 v6, v7, v6
	global_store_dword v[2:3], v6, off
	v_lshl_add_u64 v[2:3], v[2:3], 0, s[4:5]
	s_mov_b32 s18, s37
	s_add_u32 s8, s42, s10
	s_addc_u32 s9, s43, s11
	s_cmp_gt_i32 s18, 0xffff
	s_cbranch_scc0 .Lp1s_quad
	s_branch .LBB0_260
